# ml_k2 loop-header waits no longer drain the previous chunk's output stores (vmcnt 2/0 -> 18/16); gdn_k2 loads interleaved with MFMAs
# baseline (speedup 1.0000x reference)
.LBB0_465:
	s_waitcnt vmcnt(18)
	v_mov_b32_e32 v138, v119
	v_ashrrev_i32_e32 v119, 31, v118
	ds_write_b128 v133, v[2:5]
	ds_write_b128 v133, v[6:9] offset:9216
	ds_write_b128 v133, v[10:13] offset:18432
	ds_write_b128 v133, v[14:17] offset:27648
	ds_write_b128 v132, v[18:21]
	ds_write_b128 v132, v[22:25] offset:9216
	ds_write_b128 v132, v[26:29] offset:18432
	ds_write_b128 v132, v[30:33] offset:27648
	v_lshlrev_b64 v[2:3], 13, v[118:119]
	v_lshl_add_u64 v[2:3], s[30:31], 0, v[2:3]
	s_lshl_b32 s2, s41, 1
	v_lshl_add_u64 v[2:3], v[2:3], 0, s[2:3]
	v_lshl_add_u64 v[2:3], v[2:3], 0, v[0:1]
	v_add_co_u32_e32 v2, vcc, s93, v2
	v_lshl_add_u64 v[14:15], s[24:25], 0, v[112:113]
	s_nop 0
	v_addc_co_u32_e32 v3, vcc, 0, v3, vcc
	v_add_co_u32_e32 v6, vcc, s4, v14
	s_waitcnt vmcnt(16)
	v_mov_b32_e32 v121, v117
	v_addc_co_u32_e32 v7, vcc, 0, v15, vcc
	v_ashrrev_i32_e32 v117, 31, v116
	v_add_co_u32_e32 v10, vcc, s5, v14
	v_lshlrev_b64 v[18:19], 13, v[116:117]
	s_nop 0
	v_addc_co_u32_e32 v11, vcc, 0, v15, vcc
	v_lshl_add_u64 v[18:19], s[30:31], 0, v[18:19]
	v_add_co_u32_e32 v14, vcc, s6, v14
	v_lshl_add_u64 v[18:19], v[18:19], 0, s[2:3]
	s_nop 0
	v_addc_co_u32_e32 v15, vcc, 0, v15, vcc
	v_lshl_add_u64 v[18:19], v[18:19], 0, v[0:1]
	v_add_co_u32_e32 v18, vcc, s93, v18
	v_lshl_add_u64 v[30:31], s[24:25], 0, v[114:115]
	s_nop 0
	v_addc_co_u32_e32 v19, vcc, 0, v19, vcc
	v_add_co_u32_e32 v22, vcc, s4, v30
	v_lshl_add_u64 v[34:35], s[24:25], 0, v[110:111]
	s_nop 0
	v_addc_co_u32_e32 v23, vcc, 0, v31, vcc
	v_add_co_u32_e32 v26, vcc, s5, v30
	s_mov_b32 s44, 0x3000000
	s_nop 0
	v_addc_co_u32_e32 v27, vcc, 0, v31, vcc
	v_add_co_u32_e32 v30, vcc, s6, v30
	v_mov_b32_e32 v36, v134
	s_nop 0
	v_addc_co_u32_e32 v31, vcc, 0, v31, vcc
	v_add_co_u32_e32 v34, vcc, s44, v34
	v_mov_b32_e32 v66, v131
	s_nop 0
	v_addc_co_u32_e32 v35, vcc, 0, v35, vcc
	v_mov_b32_e32 v67, v130
	s_waitcnt lgkmcnt(0)
	s_barrier
	global_load_dwordx4 v[2:5], v[2:3], off offset:1552
	v_max_f32_e32 v139, v83, v83
	global_load_dwordx4 v[6:9], v[6:7], off
	s_add_u32 s44, s24, s42
	global_load_dwordx4 v[10:13], v[10:11], off
	v_mov_b32_e32 v120, v125
	global_load_dwordx4 v[14:17], v[14:15], off
	s_addc_u32 s45, s25, s43
	global_load_dwordx4 v[18:21], v[18:19], off offset:1552
	v_add_u32_e32 v136, 0x800, v127
	global_load_dwordx4 v[22:25], v[22:23], off
	v_add_u32_e32 v135, 0x1000, v127
	global_load_dwordx4 v[26:29], v[26:27], off
	v_add_u32_e32 v137, 0x1800, v127
	global_load_dwordx4 v[30:33], v[30:31], off
	s_nop 0
	global_load_dword v131, v[34:35], off offset:1280
	global_load_dword v134, v[34:35], off offset:1536
	global_load_dword v130, v[34:35], off offset:1792
	global_load_dword v119, v[34:35], off offset:2048
	v_max_f32_e32 v34, v36, v36
	v_max_f32_e32 v68, v139, v34
	v_sub_f32_e32 v34, v83, v68
	global_load_dword v125, v148, s[44:45] offset:2304
	global_load_dword v117, v148, s[44:45] offset:1532
	ds_write_b32 v128, v82 offset:36864
	v_mul_f32_e32 v69, 0x3fb8aa3b, v34
	v_sub_f32_e32 v34, v120, v68
	v_mul_f32_e32 v70, 0x3fb8aa3b, v34
	ds_read_b128 v[34:37], v129 offset:36864
	ds_read_b128 v[38:41], v129 offset:36880
	ds_read_b128 v[42:45], v129 offset:36896
	ds_read_b128 v[46:49], v129 offset:36912
	ds_read_b128 v[50:53], v107
	ds_read_b128 v[54:57], v107 offset:16
	ds_read_b128 v[58:61], v107 offset:32
	ds_read_b128 v[62:65], v107 offset:48
	s_mov_b64 s[44:45], 0x500
	s_waitcnt lgkmcnt(3)
	v_lshlrev_b32_e32 v71, 16, v50
	v_and_b32_e32 v50, 0xffff0000, v50
	v_mul_f32_e32 v35, v35, v50
	v_fmac_f32_e32 v35, v34, v71
	v_lshlrev_b32_e32 v34, 16, v51
	v_fmac_f32_e32 v35, v36, v34
	v_and_b32_e32 v34, 0xffff0000, v51
	v_fmac_f32_e32 v35, v37, v34
	v_lshlrev_b32_e32 v34, 16, v52
	v_fmac_f32_e32 v35, v38, v34
	v_and_b32_e32 v34, 0xffff0000, v52
	v_fmac_f32_e32 v35, v39, v34
	v_lshlrev_b32_e32 v34, 16, v53
	v_fmac_f32_e32 v35, v40, v34
	v_and_b32_e32 v34, 0xffff0000, v53
	v_fmac_f32_e32 v35, v41, v34
	s_waitcnt lgkmcnt(2)
	v_and_b32_e32 v36, 0xffff0000, v54
	v_add_f32_e32 v34, 0, v35
	v_lshlrev_b32_e32 v35, 16, v54
	v_mul_f32_e32 v36, v43, v36
	v_fmac_f32_e32 v36, v42, v35
	v_lshlrev_b32_e32 v35, 16, v55
	v_fmac_f32_e32 v36, v44, v35
	v_and_b32_e32 v35, 0xffff0000, v55
	v_fmac_f32_e32 v36, v45, v35
	v_lshlrev_b32_e32 v35, 16, v56
	v_fmac_f32_e32 v36, v46, v35
	v_and_b32_e32 v35, 0xffff0000, v56
	v_fmac_f32_e32 v36, v47, v35
	v_lshlrev_b32_e32 v35, 16, v57
	v_fmac_f32_e32 v36, v48, v35
	v_and_b32_e32 v35, 0xffff0000, v57
	v_fmac_f32_e32 v36, v49, v35
	v_add_f32_e32 v42, v34, v36
	ds_read_b128 v[34:37], v129 offset:36928
	ds_read_b128 v[38:41], v129 offset:36944
	s_waitcnt lgkmcnt(3)
	v_and_b32_e32 v44, 0xffff0000, v58
	v_lshlrev_b32_e32 v43, 16, v58
	v_lshl_add_u64 v[110:111], v[110:111], 0, s[44:45]
	s_waitcnt lgkmcnt(1)
	v_mul_f32_e32 v35, v35, v44
	v_fmac_f32_e32 v35, v34, v43
	v_lshlrev_b32_e32 v34, 16, v59
	v_fmac_f32_e32 v35, v36, v34
	v_and_b32_e32 v34, 0xffff0000, v59
	v_fmac_f32_e32 v35, v37, v34
	v_lshlrev_b32_e32 v34, 16, v60
	s_waitcnt lgkmcnt(0)
	v_fmac_f32_e32 v35, v38, v34
	v_and_b32_e32 v34, 0xffff0000, v60
	v_fmac_f32_e32 v35, v39, v34
	v_lshlrev_b32_e32 v34, 16, v61
	v_fmac_f32_e32 v35, v40, v34
	v_and_b32_e32 v34, 0xffff0000, v61
	v_fmac_f32_e32 v35, v41, v34
	v_add_f32_e32 v42, v42, v35
	ds_read_b128 v[34:37], v129 offset:36960
	ds_read_b128 v[38:41], v129 offset:36976
	v_and_b32_e32 v44, 0xffff0000, v62
	v_lshlrev_b32_e32 v43, 16, v62
	v_lshl_add_u64 v[112:113], v[112:113], 0, s[8:9]
	s_waitcnt lgkmcnt(1)
	v_mul_f32_e32 v35, v35, v44
	v_fmac_f32_e32 v35, v34, v43
	v_lshlrev_b32_e32 v34, 16, v63
	v_fmac_f32_e32 v35, v36, v34
	v_and_b32_e32 v34, 0xffff0000, v63
	v_fmac_f32_e32 v35, v37, v34
	v_lshlrev_b32_e32 v34, 16, v64
	s_waitcnt lgkmcnt(0)
	v_fmac_f32_e32 v35, v38, v34
	v_and_b32_e32 v34, 0xffff0000, v64
	v_fmac_f32_e32 v35, v39, v34
	v_lshlrev_b32_e32 v34, 16, v65
	v_fmac_f32_e32 v35, v40, v34
	v_and_b32_e32 v34, 0xffff0000, v65
	v_fmac_f32_e32 v35, v41, v34
	v_add_f32_e32 v46, v42, v35
	ds_read_b128 v[34:37], v107 offset:64
	ds_read_b128 v[38:41], v129 offset:36992
	ds_read_b128 v[42:45], v129 offset:37008
	v_lshl_add_u64 v[114:115], v[114:115], 0, s[8:9]
	v_add_u32_e32 v116, 64, v116
	s_waitcnt lgkmcnt(2)
	v_lshlrev_b32_e32 v47, 16, v34
	v_and_b32_e32 v34, 0xffff0000, v34
	s_waitcnt lgkmcnt(1)
	v_mul_f32_e32 v34, v39, v34
	v_fmac_f32_e32 v34, v38, v47
	v_lshlrev_b32_e32 v38, 16, v35
	v_fmac_f32_e32 v34, v40, v38
	v_and_b32_e32 v35, 0xffff0000, v35
	v_fmac_f32_e32 v34, v41, v35
	v_lshlrev_b32_e32 v35, 16, v36
	s_waitcnt lgkmcnt(0)
	v_fmac_f32_e32 v34, v42, v35
	v_and_b32_e32 v35, 0xffff0000, v36
	v_fmac_f32_e32 v34, v43, v35
	v_lshlrev_b32_e32 v35, 16, v37
	v_fmac_f32_e32 v34, v44, v35
	v_and_b32_e32 v35, 0xffff0000, v37
	v_fmac_f32_e32 v34, v45, v35
	v_add_f32_e32 v46, v46, v34
	ds_read_b128 v[34:37], v107 offset:80
	ds_read_b128 v[38:41], v129 offset:37024
	ds_read_b128 v[42:45], v129 offset:37040
	v_add_u32_e32 v118, 64, v118
	s_waitcnt lgkmcnt(2)
	v_lshlrev_b32_e32 v47, 16, v34
	v_and_b32_e32 v34, 0xffff0000, v34
	s_waitcnt lgkmcnt(1)
	v_mul_f32_e32 v34, v39, v34
	v_fmac_f32_e32 v34, v38, v47
	v_lshlrev_b32_e32 v38, 16, v35
	v_fmac_f32_e32 v34, v40, v38
	v_and_b32_e32 v35, 0xffff0000, v35
	v_fmac_f32_e32 v34, v41, v35
	v_lshlrev_b32_e32 v35, 16, v36
	s_waitcnt lgkmcnt(0)
	v_fmac_f32_e32 v34, v42, v35
	v_and_b32_e32 v35, 0xffff0000, v36
	v_fmac_f32_e32 v34, v43, v35
	v_lshlrev_b32_e32 v35, 16, v37
	v_fmac_f32_e32 v34, v44, v35
	v_and_b32_e32 v35, 0xffff0000, v37
	v_fmac_f32_e32 v34, v45, v35
	v_add_f32_e32 v46, v46, v34
	ds_read_b128 v[34:37], v107 offset:96
	ds_read_b128 v[38:41], v129 offset:37056
	ds_read_b128 v[42:45], v129 offset:37072
	s_waitcnt lgkmcnt(2)
	v_lshlrev_b32_e32 v47, 16, v34
	v_and_b32_e32 v34, 0xffff0000, v34
	s_waitcnt lgkmcnt(1)
	v_mul_f32_e32 v34, v39, v34
	v_fmac_f32_e32 v34, v38, v47
	v_lshlrev_b32_e32 v38, 16, v35
	v_fmac_f32_e32 v34, v40, v38
	v_and_b32_e32 v35, 0xffff0000, v35
	v_fmac_f32_e32 v34, v41, v35
	v_lshlrev_b32_e32 v35, 16, v36
	s_waitcnt lgkmcnt(0)
	v_fmac_f32_e32 v34, v42, v35
	v_and_b32_e32 v35, 0xffff0000, v36
	v_fmac_f32_e32 v34, v43, v35
	v_lshlrev_b32_e32 v35, 16, v37
	v_fmac_f32_e32 v34, v44, v35
	v_and_b32_e32 v35, 0xffff0000, v37
	v_fmac_f32_e32 v34, v45, v35
	v_add_f32_e32 v46, v46, v34
	ds_read_b128 v[34:37], v107 offset:112
	ds_read_b128 v[38:41], v129 offset:37088
	ds_read_b128 v[42:45], v129 offset:37104
	s_waitcnt lgkmcnt(2)
	v_lshlrev_b32_e32 v47, 16, v34
	v_and_b32_e32 v34, 0xffff0000, v34
	s_waitcnt lgkmcnt(1)
	v_mul_f32_e32 v34, v39, v34
	v_fmac_f32_e32 v34, v38, v47
	v_lshlrev_b32_e32 v38, 16, v35
	v_fmac_f32_e32 v34, v40, v38
	v_and_b32_e32 v35, 0xffff0000, v35
	v_fmac_f32_e32 v34, v41, v35
	v_lshlrev_b32_e32 v35, 16, v36
	s_waitcnt lgkmcnt(0)
	v_fmac_f32_e32 v34, v42, v35
	v_and_b32_e32 v35, 0xffff0000, v36
	v_fmac_f32_e32 v34, v43, v35
	v_lshlrev_b32_e32 v35, 16, v37
	v_fmac_f32_e32 v34, v44, v35
	v_and_b32_e32 v35, 0xffff0000, v37
	v_fmac_f32_e32 v34, v45, v35
	v_exp_f32_e32 v35, v69
	v_add_f32_e32 v37, v68, v66
	v_exp_f32_e32 v36, v70
	v_mul_f32_e32 v37, 0xbfb8aa3b, v37
	v_exp_f32_e32 v37, v37
	v_add_f32_e32 v34, v46, v34
	v_mul_f32_e32 v34, v35, v34
	v_fmac_f32_e32 v34, v67, v36
	v_max_f32_e64 v34, |v34|, v37
	v_rcp_f32_e32 v34, v34
	v_cvt_pk_bf16_f32 v37, v94, v95
	v_mul_f32_e32 v35, v35, v34
	v_mul_f32_e32 v34, v36, v34
	ds_write2st64_b32 v128, v35, v34 offset0:145 offset1:146
	ds_read2_b64 v[38:41], v127 offset1:4
	ds_read2_b64 v[42:45], v136 offset0:32 offset1:36
	ds_read2_b64 v[46:49], v135 offset0:64 offset1:68
	ds_read2_b64 v[50:53], v137 offset0:96 offset1:100
	ds_read2_b64 v[54:57], v127 offset0:8 offset1:12
	v_cvt_pk_bf16_f32 v34, v96, v97
	v_cvt_pk_bf16_f32 v35, v98, v99
	v_cvt_pk_bf16_f32 v36, v92, v93
	s_waitcnt lgkmcnt(4)
	s_nop 0
	v_mfma_f32_16x16x32_bf16 v[38:41], v[38:41], v[34:37], 0
	s_waitcnt lgkmcnt(3)
	v_mfma_f32_16x16x32_bf16 v[42:45], v[42:45], v[34:37], 0
	s_waitcnt lgkmcnt(2)
	v_mfma_f32_16x16x32_bf16 v[46:49], v[46:49], v[34:37], 0
	s_waitcnt lgkmcnt(1)
	v_mfma_f32_16x16x32_bf16 v[34:37], v[50:53], v[34:37], 0
	v_cvt_pk_bf16_f32 v50, v88, v89
	v_cvt_pk_bf16_f32 v51, v90, v91
	v_cvt_pk_bf16_f32 v52, v84, v85
	v_cvt_pk_bf16_f32 v53, v86, v87
	s_waitcnt lgkmcnt(0)
	s_nop 0
	v_mfma_f32_16x16x32_bf16 v[74:77], v[54:57], v[50:53], v[38:41]
	s_nop 2
	ds_read2_b64 v[38:41], v136 offset0:40 offset1:44
	s_waitcnt lgkmcnt(0)
	v_mfma_f32_16x16x32_bf16 v[66:69], v[38:41], v[50:53], v[42:45]
	ds_read2_b64 v[38:41], v135 offset0:72 offset1:76
	s_waitcnt lgkmcnt(0)
	v_mfma_f32_16x16x32_bf16 v[58:61], v[38:41], v[50:53], v[46:49]
	ds_read2_b64 v[38:41], v137 offset0:104 offset1:108
	s_waitcnt lgkmcnt(0)
	v_mfma_f32_16x16x32_bf16 v[34:37], v[38:41], v[50:53], v[34:37]
	ds_read_b128 v[38:41], v102 offset:27648
	ds_read_b128 v[42:45], v100 offset:9216
	ds_read_b128 v[46:49], v100 offset:11520
	ds_read_b128 v[50:53], v100 offset:13824
	ds_read_b128 v[54:57], v100 offset:16128
	ds_read_b128 v[140:143], v102 offset:27712
	ds_read_b128 v[62:65], v100 offset:9280
	ds_read_b128 v[70:73], v100 offset:11584
	ds_read_b128 v[164:167], v100 offset:13888
	ds_read_b128 v[168:171], v100 offset:16192
	s_waitcnt lgkmcnt(8)
	v_mfma_f32_16x16x32_bf16 v[42:45], v[42:45], v[38:41], 0
	s_waitcnt lgkmcnt(7)
	v_mfma_f32_16x16x32_bf16 v[46:49], v[46:49], v[38:41], 0
	s_waitcnt lgkmcnt(6)
	v_mfma_f32_16x16x32_bf16 v[50:53], v[50:53], v[38:41], 0
	s_waitcnt lgkmcnt(3)
	v_mfma_f32_16x16x32_bf16 v[172:175], v[62:65], v[140:143], v[42:45]
	s_waitcnt lgkmcnt(2)
	v_mfma_f32_16x16x32_bf16 v[70:73], v[70:73], v[140:143], v[46:49]
	s_waitcnt lgkmcnt(1)
	v_mfma_f32_16x16x32_bf16 v[62:65], v[164:167], v[140:143], v[50:53]
	ds_read_b128 v[42:45], v100 offset:18432
	ds_read_b128 v[46:49], v100 offset:20736
	s_nop 0
	ds_read_b128 v[50:53], v100 offset:23040
	ds_read_b128 v[164:167], v100 offset:25344
	v_mfma_f32_16x16x32_bf16 v[54:57], v[54:57], v[38:41], 0
	s_waitcnt lgkmcnt(4)
	v_mfma_f32_16x16x32_bf16 v[54:57], v[168:171], v[140:143], v[54:57]
	s_waitcnt lgkmcnt(3)
	v_mfma_f32_16x16x32_bf16 v[42:45], v[42:45], v[38:41], 0
	s_waitcnt lgkmcnt(2)
	v_mfma_f32_16x16x32_bf16 v[46:49], v[46:49], v[38:41], 0
	s_waitcnt lgkmcnt(1)
	v_mfma_f32_16x16x32_bf16 v[168:171], v[50:53], v[38:41], 0
	s_waitcnt lgkmcnt(0)
	v_mfma_f32_16x16x32_bf16 v[38:41], v[164:167], v[38:41], 0
	ds_read_b128 v[50:53], v100 offset:18496
	ds_read_b128 v[164:167], v100 offset:20800
	ds_read_b128 v[176:179], v100 offset:23104
	ds_read_b128 v[180:183], v100 offset:25408
	s_waitcnt lgkmcnt(3)
	v_mfma_f32_16x16x32_bf16 v[50:53], v[50:53], v[140:143], v[42:45]
	s_waitcnt lgkmcnt(2)
	v_mfma_f32_16x16x32_bf16 v[46:49], v[164:167], v[140:143], v[46:49]
	s_waitcnt lgkmcnt(1)
	v_mfma_f32_16x16x32_bf16 v[42:45], v[176:179], v[140:143], v[168:171]
	v_add_u32_e32 v176, s0, v106
	s_waitcnt lgkmcnt(0)
	v_mfma_f32_16x16x32_bf16 v[38:41], v[180:183], v[140:143], v[38:41]
	ds_read_b128 v[140:143], v103 offset:37120
	ds_read_b128 v[164:167], v103 offset:37376
	v_lshl_add_u64 v[168:169], v[108:109], 0, s[0:1]
	v_add_co_u32_e32 v170, vcc, s87, v168
	s_waitcnt lgkmcnt(0)
	v_mul_f32_e32 v164, v172, v164
	v_fmac_f32_e32 v164, v74, v140
	v_cvt_pk_bf16_f32 v74, v164, s0
	v_addc_co_u32_e32 v171, vcc, 0, v169, vcc
	global_store_short v[170:171], v74, off offset:2560
	v_mul_f32_e32 v74, v173, v165
	v_fmac_f32_e32 v74, v75, v141
	v_cvt_pk_bf16_f32 v140, v74, s0
	v_add_co_u32_e32 v74, vcc, s29, v168
	v_or_b32_e32 v164, 0x20000, v176
	s_nop 0
	v_addc_co_u32_e32 v75, vcc, 0, v169, vcc
	global_store_short v[74:75], v140, off offset:2560
	v_mul_f32_e32 v74, v174, v166
	v_fmac_f32_e32 v74, v76, v142
	v_cvt_pk_bf16_f32 v76, v74, s0
	v_add_co_u32_e32 v74, vcc, s33, v168
	v_mov_b32_e32 v165, v1
	s_nop 0
	v_addc_co_u32_e32 v75, vcc, 0, v169, vcc
	global_store_short v[74:75], v76, off offset:2560
	v_mul_f32_e32 v74, v175, v167
	v_fmac_f32_e32 v74, v77, v143
	v_cvt_pk_bf16_f32 v76, v74, s0
	v_add_co_u32_e32 v74, vcc, s88, v168
	v_lshl_add_u64 v[164:165], v[104:105], 0, v[164:165]
	s_nop 0
	v_addc_co_u32_e32 v75, vcc, 0, v169, vcc
	global_store_short v[74:75], v76, off offset:2560
	ds_read_b128 v[74:77], v103 offset:37184
	ds_read_b128 v[140:143], v103 offset:37440
	s_waitcnt lgkmcnt(0)
	v_mul_f32_e32 v70, v70, v140
	v_fmac_f32_e32 v70, v66, v74
	v_cvt_pk_bf16_f32 v66, v70, s0
	global_store_short v[164:165], v66, off offset:2560
	v_mul_f32_e32 v66, v71, v141
	v_fmac_f32_e32 v66, v67, v75
	v_cvt_pk_bf16_f32 v70, v66, s0
	v_add_co_u32_e32 v66, vcc, s94, v164
	v_or_b32_e32 v74, 0x40000, v176
	s_nop 0
	v_addc_co_u32_e32 v67, vcc, 0, v165, vcc
	global_store_short v[66:67], v70, off offset:2560
	v_mul_f32_e32 v66, v72, v142
	v_fmac_f32_e32 v66, v68, v76
	v_cvt_pk_bf16_f32 v68, v66, s0
	v_add_co_u32_e32 v66, vcc, s86, v164
	v_mov_b32_e32 v75, v1
	s_nop 0
	v_addc_co_u32_e32 v67, vcc, 0, v165, vcc
	global_store_short v[66:67], v68, off offset:2560
	v_mul_f32_e32 v66, v73, v143
	v_fmac_f32_e32 v66, v69, v77
	v_cvt_pk_bf16_f32 v68, v66, s0
	v_add_co_u32_e32 v66, vcc, s82, v164
	v_lshl_add_u64 v[74:75], v[104:105], 0, v[74:75]
	s_nop 0
	v_addc_co_u32_e32 v67, vcc, 0, v165, vcc
	global_store_short v[66:67], v68, off offset:2560
	ds_read_b128 v[66:69], v103 offset:37248
	ds_read_b128 v[70:73], v103 offset:37504
	s_waitcnt lgkmcnt(0)
	v_mul_f32_e32 v62, v62, v70
	v_fmac_f32_e32 v62, v58, v66
	v_cvt_pk_bf16_f32 v58, v62, s0
	global_store_short v[74:75], v58, off offset:2560
	v_mul_f32_e32 v58, v63, v71
	v_fmac_f32_e32 v58, v59, v67
	v_cvt_pk_bf16_f32 v62, v58, s0
	v_add_co_u32_e32 v58, vcc, s94, v74
	v_or_b32_e32 v66, 0x60000, v176
	s_nop 0
	v_addc_co_u32_e32 v59, vcc, 0, v75, vcc
	global_store_short v[58:59], v62, off offset:2560
	v_mul_f32_e32 v58, v64, v72
	v_fmac_f32_e32 v58, v60, v68
	v_cvt_pk_bf16_f32 v60, v58, s0
	v_add_co_u32_e32 v58, vcc, s86, v74
	v_mov_b32_e32 v67, v1
	s_nop 0
	v_addc_co_u32_e32 v59, vcc, 0, v75, vcc
	global_store_short v[58:59], v60, off offset:2560
	v_mul_f32_e32 v58, v65, v73
	v_fmac_f32_e32 v58, v61, v69
	v_cvt_pk_bf16_f32 v60, v58, s0
	v_add_co_u32_e32 v58, vcc, s82, v74
	v_lshl_add_u64 v[66:67], v[104:105], 0, v[66:67]
	s_nop 0
	v_addc_co_u32_e32 v59, vcc, 0, v75, vcc
	global_store_short v[58:59], v60, off offset:2560
	ds_read_b128 v[58:61], v103 offset:37312
	ds_read_b128 v[62:65], v103 offset:37568
	s_waitcnt lgkmcnt(0)
	v_mul_f32_e32 v54, v54, v62
	v_fmac_f32_e32 v54, v34, v58
	v_cvt_pk_bf16_f32 v34, v54, s0
	global_store_short v[66:67], v34, off offset:2560
	v_mul_f32_e32 v34, v55, v63
	v_fmac_f32_e32 v34, v35, v59
	v_cvt_pk_bf16_f32 v54, v34, s0
	v_add_co_u32_e32 v34, vcc, s94, v66
	s_nop 1
	v_addc_co_u32_e32 v35, vcc, 0, v67, vcc
	global_store_short v[34:35], v54, off offset:2560
	v_mul_f32_e32 v34, v56, v64
	v_fmac_f32_e32 v34, v36, v60
	v_cvt_pk_bf16_f32 v36, v34, s0
	v_add_co_u32_e32 v34, vcc, s86, v66
	s_nop 1
	v_addc_co_u32_e32 v35, vcc, 0, v67, vcc
	global_store_short v[34:35], v36, off offset:2560
	v_mul_f32_e32 v34, v57, v65
	v_fmac_f32_e32 v34, v37, v61
	v_cvt_pk_bf16_f32 v36, v34, s0
	v_add_co_u32_e32 v34, vcc, s82, v66
	s_add_u32 s0, s0, 0x80000
	s_nop 0
	v_addc_co_u32_e32 v35, vcc, 0, v67, vcc
	global_store_short v[34:35], v36, off offset:2560
	v_max_f32_e32 v34, v120, v120
	v_max_f32_e32 v35, v139, v34
	v_sub_f32_e32 v36, v120, v35
	v_sub_f32_e32 v34, v83, v35
	v_mul_f32_e32 v36, 0x3fb8aa3b, v36
	v_mul_f32_e32 v34, 0x3fb8aa3b, v34
	v_exp_f32_e32 v36, v36
	v_exp_f32_e32 v34, v34
	s_addc_u32 s1, s1, 0
	s_add_u32 s42, s42, 0x500
	v_pk_mul_f32 v[52:53], v[36:37], v[52:53] op_sel_hi:[0,1]
	v_pk_mul_f32 v[50:51], v[36:37], v[50:51] op_sel_hi:[0,1]
	v_pk_mul_f32 v[48:49], v[36:37], v[48:49] op_sel_hi:[0,1]
	v_pk_mul_f32 v[46:47], v[36:37], v[46:47] op_sel_hi:[0,1]
	v_pk_mul_f32 v[44:45], v[36:37], v[44:45] op_sel_hi:[0,1]
	v_pk_mul_f32 v[42:43], v[36:37], v[42:43] op_sel_hi:[0,1]
	v_pk_mul_f32 v[40:41], v[36:37], v[40:41] op_sel_hi:[0,1]
	v_pk_mul_f32 v[38:39], v[36:37], v[38:39] op_sel_hi:[0,1]
	v_pk_fma_f32 v[98:99], v[98:99], v[34:35], v[52:53] op_sel_hi:[1,0,1]
	v_pk_fma_f32 v[96:97], v[96:97], v[34:35], v[50:51] op_sel_hi:[1,0,1]
	v_pk_fma_f32 v[94:95], v[94:95], v[34:35], v[48:49] op_sel_hi:[1,0,1]
	v_pk_fma_f32 v[92:93], v[92:93], v[34:35], v[46:47] op_sel_hi:[1,0,1]
	v_pk_fma_f32 v[90:91], v[90:91], v[34:35], v[44:45] op_sel_hi:[1,0,1]
	v_pk_fma_f32 v[88:89], v[88:89], v[34:35], v[42:43] op_sel_hi:[1,0,1]
	v_pk_fma_f32 v[86:87], v[86:87], v[34:35], v[40:41] op_sel_hi:[1,0,1]
	v_pk_fma_f32 v[84:85], v[84:85], v[34:35], v[38:39] op_sel_hi:[1,0,1]
	v_mul_f32_e32 v120, v82, v34
	v_mul_f32_e32 v34, v138, v36
	s_addc_u32 s43, s43, 0
	v_pk_add_f32 v[82:83], v[120:121], v[34:35]
	s_cmp_eq_u32 s0, 0xf80000
	s_barrier
	s_cbranch_scc0 .LBB0_465
	s_waitcnt vmcnt(20)
	v_max_f32_e32 v0, v134, v134
	v_max_f32_e32 v44, v83, v83
	v_max_f32_e32 v0, v44, v0
	ds_write_b128 v133, v[2:5]
	ds_write_b128 v133, v[6:9] offset:9216
	ds_write_b128 v133, v[10:13] offset:18432
	ds_write_b128 v133, v[14:17] offset:27648
	ds_write_b128 v132, v[18:21]
	ds_write_b128 v132, v[22:25] offset:9216
	ds_write_b128 v132, v[26:29] offset:18432
	ds_write_b128 v132, v[30:33] offset:27648
	v_sub_f32_e32 v2, v83, v0
	s_waitcnt lgkmcnt(0)
	s_barrier
	ds_write_b32 v128, v82 offset:36864
	v_mul_f32_e32 v34, 0x3fb8aa3b, v2
	s_waitcnt vmcnt(17)
	v_sub_f32_e32 v2, v125, v0
	v_mul_f32_e32 v35, 0x3fb8aa3b, v2
	ds_read_b128 v[2:5], v129 offset:36864
	ds_read_b128 v[6:9], v129 offset:36880
	ds_read_b128 v[10:13], v129 offset:36896
	ds_read_b128 v[14:17], v107
	ds_read_b128 v[18:21], v129 offset:36912
	ds_read_b128 v[22:25], v107 offset:16
	ds_read_b128 v[26:29], v107 offset:32
	ds_read_b128 v[30:33], v107 offset:48
	s_waitcnt lgkmcnt(4)
	v_lshlrev_b32_e32 v36, 16, v14
	v_and_b32_e32 v14, 0xffff0000, v14
	v_mul_f32_e32 v3, v3, v14
	v_fmac_f32_e32 v3, v2, v36
	v_lshlrev_b32_e32 v2, 16, v15
	v_fmac_f32_e32 v3, v4, v2
	v_and_b32_e32 v2, 0xffff0000, v15
	v_fmac_f32_e32 v3, v5, v2
	v_lshlrev_b32_e32 v2, 16, v16
	v_fmac_f32_e32 v3, v6, v2
	v_and_b32_e32 v2, 0xffff0000, v16
	v_fmac_f32_e32 v3, v7, v2
	v_lshlrev_b32_e32 v2, 16, v17
	v_fmac_f32_e32 v3, v8, v2
	v_and_b32_e32 v2, 0xffff0000, v17
	v_fmac_f32_e32 v3, v9, v2
	v_add_f32_e32 v6, 0, v3
	s_waitcnt lgkmcnt(2)
	v_and_b32_e32 v3, 0xffff0000, v22
	v_lshlrev_b32_e32 v2, 16, v22
	v_mul_f32_e32 v7, v11, v3
	v_fmac_f32_e32 v7, v10, v2
	v_lshlrev_b32_e32 v2, 16, v23
	v_fmac_f32_e32 v7, v12, v2
	v_and_b32_e32 v2, 0xffff0000, v23
	v_fmac_f32_e32 v7, v13, v2
	v_lshlrev_b32_e32 v2, 16, v24
	v_fmac_f32_e32 v7, v18, v2
	v_and_b32_e32 v2, 0xffff0000, v24
	v_fmac_f32_e32 v7, v19, v2
	v_lshlrev_b32_e32 v2, 16, v25
	v_fmac_f32_e32 v7, v20, v2
	v_and_b32_e32 v2, 0xffff0000, v25
	v_fmac_f32_e32 v7, v21, v2
	ds_read_b128 v[2:5], v129 offset:36928
	v_add_f32_e32 v10, v6, v7
	ds_read_b128 v[6:9], v129 offset:36944
	s_waitcnt lgkmcnt(3)
	v_and_b32_e32 v12, 0xffff0000, v26
	v_lshlrev_b32_e32 v11, 16, v26
	s_waitcnt lgkmcnt(1)
	v_mul_f32_e32 v12, v3, v12
	v_fmac_f32_e32 v12, v2, v11
	v_lshlrev_b32_e32 v2, 16, v27
	v_fmac_f32_e32 v12, v4, v2
	v_and_b32_e32 v2, 0xffff0000, v27
	v_fmac_f32_e32 v12, v5, v2
	v_lshlrev_b32_e32 v2, 16, v28
	s_waitcnt lgkmcnt(0)
	v_fmac_f32_e32 v12, v6, v2
	v_and_b32_e32 v2, 0xffff0000, v28
	v_fmac_f32_e32 v12, v7, v2
	v_lshlrev_b32_e32 v2, 16, v29
	v_fmac_f32_e32 v12, v8, v2
	v_and_b32_e32 v2, 0xffff0000, v29
	v_fmac_f32_e32 v12, v9, v2
	ds_read_b128 v[2:5], v129 offset:36960
	ds_read_b128 v[6:9], v129 offset:36976
	v_add_f32_e32 v10, v10, v12
	v_and_b32_e32 v12, 0xffff0000, v30
	v_lshlrev_b32_e32 v11, 16, v30
	s_waitcnt lgkmcnt(1)
	v_mul_f32_e32 v12, v3, v12
	v_fmac_f32_e32 v12, v2, v11
	v_lshlrev_b32_e32 v2, 16, v31
	v_fmac_f32_e32 v12, v4, v2
	v_and_b32_e32 v2, 0xffff0000, v31
	v_fmac_f32_e32 v12, v5, v2
	v_lshlrev_b32_e32 v2, 16, v32
	s_waitcnt lgkmcnt(0)
	v_fmac_f32_e32 v12, v6, v2
	v_and_b32_e32 v2, 0xffff0000, v32
	v_fmac_f32_e32 v12, v7, v2
	v_lshlrev_b32_e32 v2, 16, v33
	v_fmac_f32_e32 v12, v8, v2
	v_and_b32_e32 v6, 0xffff0000, v33
	ds_read_b128 v[2:5], v107 offset:64
	v_fmac_f32_e32 v12, v9, v6
	ds_read_b128 v[6:9], v129 offset:36992
	v_add_f32_e32 v14, v10, v12
	ds_read_b128 v[10:13], v129 offset:37008
	s_waitcnt lgkmcnt(2)
	v_lshlrev_b32_e32 v15, 16, v2
	v_and_b32_e32 v2, 0xffff0000, v2
	s_waitcnt lgkmcnt(1)
	v_mul_f32_e32 v16, v7, v2
	v_fmac_f32_e32 v16, v6, v15
	v_lshlrev_b32_e32 v2, 16, v3
	v_fmac_f32_e32 v16, v8, v2
	v_and_b32_e32 v2, 0xffff0000, v3
	v_fmac_f32_e32 v16, v9, v2
	v_lshlrev_b32_e32 v2, 16, v4
	s_waitcnt lgkmcnt(0)
	v_fmac_f32_e32 v16, v10, v2
	v_and_b32_e32 v2, 0xffff0000, v4
	v_fmac_f32_e32 v16, v11, v2
	v_lshlrev_b32_e32 v2, 16, v5
	v_fmac_f32_e32 v16, v12, v2
	v_and_b32_e32 v6, 0xffff0000, v5
	ds_read_b128 v[2:5], v107 offset:80
	v_fmac_f32_e32 v16, v13, v6
	ds_read_b128 v[6:9], v129 offset:37024
	ds_read_b128 v[10:13], v129 offset:37040
	v_add_f32_e32 v14, v14, v16
	s_waitcnt lgkmcnt(2)
	v_lshlrev_b32_e32 v15, 16, v2
	v_and_b32_e32 v2, 0xffff0000, v2
	s_waitcnt lgkmcnt(1)
	v_mul_f32_e32 v16, v7, v2
	v_fmac_f32_e32 v16, v6, v15
	v_lshlrev_b32_e32 v2, 16, v3
	v_fmac_f32_e32 v16, v8, v2
	v_and_b32_e32 v2, 0xffff0000, v3
	v_fmac_f32_e32 v16, v9, v2
	v_lshlrev_b32_e32 v2, 16, v4
	s_waitcnt lgkmcnt(0)
	v_fmac_f32_e32 v16, v10, v2
	v_and_b32_e32 v2, 0xffff0000, v4
	v_fmac_f32_e32 v16, v11, v2
	v_lshlrev_b32_e32 v2, 16, v5
	v_fmac_f32_e32 v16, v12, v2
	v_and_b32_e32 v6, 0xffff0000, v5
	ds_read_b128 v[2:5], v107 offset:96
	v_fmac_f32_e32 v16, v13, v6
	ds_read_b128 v[6:9], v129 offset:37056
	ds_read_b128 v[10:13], v129 offset:37072
	v_add_f32_e32 v14, v14, v16
	s_waitcnt lgkmcnt(2)
	v_lshlrev_b32_e32 v15, 16, v2
	v_and_b32_e32 v2, 0xffff0000, v2
	s_waitcnt lgkmcnt(1)
	v_mul_f32_e32 v16, v7, v2
	v_fmac_f32_e32 v16, v6, v15
	v_lshlrev_b32_e32 v2, 16, v3
	v_fmac_f32_e32 v16, v8, v2
	v_and_b32_e32 v2, 0xffff0000, v3
	v_fmac_f32_e32 v16, v9, v2
	v_lshlrev_b32_e32 v2, 16, v4
	s_waitcnt lgkmcnt(0)
	v_fmac_f32_e32 v16, v10, v2
	v_and_b32_e32 v2, 0xffff0000, v4
	v_fmac_f32_e32 v16, v11, v2
	v_lshlrev_b32_e32 v2, 16, v5
	v_fmac_f32_e32 v16, v12, v2
	v_and_b32_e32 v6, 0xffff0000, v5
	ds_read_b128 v[2:5], v107 offset:112
	v_fmac_f32_e32 v16, v13, v6
	ds_read_b128 v[6:9], v129 offset:37088
	ds_read_b128 v[10:13], v129 offset:37104
	v_add_f32_e32 v0, v131, v0
	s_waitcnt lgkmcnt(2)
	v_lshlrev_b32_e32 v15, 16, v2
	v_and_b32_e32 v2, 0xffff0000, v2
	s_waitcnt lgkmcnt(1)
	v_mul_f32_e32 v2, v7, v2
	v_fmac_f32_e32 v2, v6, v15
	v_lshlrev_b32_e32 v6, 16, v3
	v_fmac_f32_e32 v2, v8, v6
	v_and_b32_e32 v3, 0xffff0000, v3
	v_fmac_f32_e32 v2, v9, v3
	v_lshlrev_b32_e32 v3, 16, v4
	s_waitcnt lgkmcnt(0)
	v_fmac_f32_e32 v2, v10, v3
	v_and_b32_e32 v3, 0xffff0000, v4
	v_fmac_f32_e32 v2, v11, v3
	v_lshlrev_b32_e32 v3, 16, v5
	v_fmac_f32_e32 v2, v12, v3
	v_and_b32_e32 v3, 0xffff0000, v5
	v_fmac_f32_e32 v2, v13, v3
	v_exp_f32_e32 v3, v34
	v_exp_f32_e32 v4, v35
	v_mul_f32_e32 v0, 0xbfb8aa3b, v0
	v_add_f32_e32 v14, v14, v16
	v_exp_f32_e32 v0, v0
	v_add_f32_e32 v2, v14, v2
	v_mul_f32_e32 v2, v3, v2
	v_fmac_f32_e32 v2, v130, v4
	v_max_f32_e64 v0, |v2|, v0
	v_rcp_f32_e32 v0, v0
	v_cvt_pk_bf16_f32 v10, v96, v97
	v_cvt_pk_bf16_f32 v11, v98, v99
	v_cvt_pk_bf16_f32 v12, v92, v93
	v_mul_f32_e32 v2, v3, v0
	v_mul_f32_e32 v0, v4, v0
	ds_write2st64_b32 v128, v2, v0 offset0:145 offset1:146
	ds_read2_b64 v[2:5], v127 offset1:4
	ds_read2_b64 v[6:9], v136 offset0:32 offset1:36
	ds_read2_b64 v[14:17], v135 offset0:64 offset1:68
	ds_read2_b64 v[18:21], v137 offset0:96 offset1:100
	ds_read2_b64 v[22:25], v127 offset0:8 offset1:12
	v_cvt_pk_bf16_f32 v13, v94, v95
	v_cvt_pk_bf16_f32 v34, v88, v89
	v_cvt_pk_bf16_f32 v35, v90, v91
	s_waitcnt lgkmcnt(4)
	v_mfma_f32_16x16x32_bf16 v[2:5], v[2:5], v[10:13], 0
	v_cvt_pk_bf16_f32 v36, v84, v85
	v_cvt_pk_bf16_f32 v37, v86, v87
	v_or_b32_e32 v0, s39, v126
	s_waitcnt lgkmcnt(3)
	v_mfma_f32_16x16x32_bf16 v[6:9], v[6:9], v[10:13], 0
	v_lshlrev_b32_e32 v0, 13, v0
	v_lshl_add_u64 v[42:43], s[30:31], 0, v[0:1]
	v_lshl_add_u64 v[42:43], v[42:43], 0, s[2:3]
	s_waitcnt lgkmcnt(2)
	v_mfma_f32_16x16x32_bf16 v[14:17], v[14:17], v[10:13], 0
	v_lshl_add_u64 v[42:43], v[80:81], 1, v[42:43]
	v_readlane_b32 s2, v239, 11
	v_readlane_b32 s4, v239, 12
	s_waitcnt lgkmcnt(1)
	v_mfma_f32_16x16x32_bf16 v[10:13], v[18:21], v[10:13], 0
	ds_read2_b64 v[18:21], v136 offset0:40 offset1:44
	s_waitcnt lgkmcnt(1)
	v_mfma_f32_16x16x32_bf16 v[46:49], v[22:25], v[34:37], v[2:5]
	s_nop 2
	ds_read2_b64 v[2:5], v135 offset0:72 offset1:76
	s_waitcnt lgkmcnt(1)
	v_mfma_f32_16x16x32_bf16 v[30:33], v[18:21], v[34:37], v[6:9]
	ds_read_b128 v[18:21], v100 offset:13824
	s_nop 1
	ds_read2_b64 v[6:9], v137 offset0:104 offset1:108
	s_waitcnt lgkmcnt(2)
	v_mfma_f32_16x16x32_bf16 v[26:29], v[2:5], v[34:37], v[14:17]
	s_nop 2
	ds_read_b128 v[14:17], v100 offset:9216
	s_waitcnt lgkmcnt(1)
	v_mfma_f32_16x16x32_bf16 v[2:5], v[6:9], v[34:37], v[10:13]
	s_nop 2
	ds_read_b128 v[10:13], v102 offset:27648
	s_waitcnt lgkmcnt(0)
	v_mfma_f32_16x16x32_bf16 v[6:9], v[14:17], v[10:13], 0
	ds_read_b128 v[14:17], v100 offset:11520
	ds_read_b128 v[22:25], v100 offset:16128
	ds_read_b128 v[34:37], v100 offset:9280
	ds_read_b128 v[50:53], v102 offset:27712
	ds_read_b128 v[38:41], v100 offset:11584
	s_waitcnt lgkmcnt(4)
	v_mfma_f32_16x16x32_bf16 v[14:17], v[14:17], v[10:13], 0
	ds_read_b128 v[58:61], v100 offset:25344
	ds_read_b128 v[62:65], v100 offset:18496
	ds_read_b128 v[66:69], v100 offset:20800
	s_waitcnt lgkmcnt(4)
	v_mfma_f32_16x16x32_bf16 v[54:57], v[34:37], v[50:53], v[6:9]
	s_nop 2
	ds_read_b128 v[6:9], v100 offset:13888
	s_waitcnt lgkmcnt(4)
	v_mfma_f32_16x16x32_bf16 v[38:41], v[38:41], v[50:53], v[14:17]
	s_nop 2
	ds_read_b128 v[14:17], v100 offset:16192
	v_mfma_f32_16x16x32_bf16 v[18:21], v[18:21], v[10:13], 0
	v_mfma_f32_16x16x32_bf16 v[22:25], v[22:25], v[10:13], 0
	s_waitcnt lgkmcnt(1)
	v_mfma_f32_16x16x32_bf16 v[34:37], v[6:9], v[50:53], v[18:21]
	s_nop 4
	ds_read_b128 v[18:21], v100 offset:18432
	s_waitcnt lgkmcnt(1)
	v_mfma_f32_16x16x32_bf16 v[6:9], v[14:17], v[50:53], v[22:25]
	ds_read_b128 v[14:17], v100 offset:20736
	s_nop 1
	ds_read_b128 v[22:25], v100 offset:23040
	s_waitcnt lgkmcnt(2)
	v_mfma_f32_16x16x32_bf16 v[18:21], v[18:21], v[10:13], 0
	s_waitcnt lgkmcnt(1)
	v_mfma_f32_16x16x32_bf16 v[14:17], v[14:17], v[10:13], 0
	s_waitcnt lgkmcnt(0)
	v_mfma_f32_16x16x32_bf16 v[22:25], v[22:25], v[10:13], 0
	v_mfma_f32_16x16x32_bf16 v[58:61], v[58:61], v[10:13], 0
	v_mfma_f32_16x16x32_bf16 v[10:13], v[62:65], v[50:53], v[18:21]
	ds_read_b128 v[62:65], v100 offset:25408
	s_nop 1
	ds_read_b128 v[18:21], v100 offset:23104
	v_mfma_f32_16x16x32_bf16 v[14:17], v[66:69], v[50:53], v[14:17]
	ds_read_b128 v[66:69], v103 offset:37376
	ds_read_b128 v[70:73], v103 offset:37120
	s_waitcnt lgkmcnt(1)
	v_mul_f32_e32 v0, v54, v66
	s_waitcnt lgkmcnt(0)
	v_fmac_f32_e32 v0, v46, v70
	v_cvt_pk_bf16_f32 v0, v0, s0
	s_mov_b32 s0, 0xf80000
	v_mfma_f32_16x16x32_bf16 v[18:21], v[18:21], v[50:53], v[22:25]
	v_mfma_f32_16x16x32_bf16 v[22:25], v[62:65], v[50:53], v[58:61]
	v_add_co_u32_e32 v50, vcc, s0, v42
	s_nop 1
	v_addc_co_u32_e32 v51, vcc, 0, v43, vcc
	global_store_short v[50:51], v0, off offset:2560
	v_mul_f32_e32 v0, v55, v67
	v_fmac_f32_e32 v0, v47, v71
	v_cvt_pk_bf16_f32 v0, v0, s0
	s_mov_b32 s0, 0xf82000
	v_add_co_u32_e32 v46, vcc, s0, v42
	s_nop 1
	v_addc_co_u32_e32 v47, vcc, 0, v43, vcc
	global_store_short v[46:47], v0, off offset:2560
	v_mul_f32_e32 v0, v56, v68
	v_fmac_f32_e32 v0, v48, v72
	v_cvt_pk_bf16_f32 v0, v0, s0
	s_mov_b32 s0, 0xf84000
	v_add_co_u32_e32 v46, vcc, s0, v42
	s_nop 1
	v_addc_co_u32_e32 v47, vcc, 0, v43, vcc
	global_store_short v[46:47], v0, off offset:2560
	v_mul_f32_e32 v0, v57, v69
	v_fmac_f32_e32 v0, v49, v73
	ds_read_b128 v[46:49], v103 offset:37440
	ds_read_b128 v[50:53], v103 offset:37184
	v_cvt_pk_bf16_f32 v0, v0, s0
	s_mov_b32 s0, 0xf86000
	v_add_co_u32_e32 v54, vcc, s0, v42
	s_nop 1
	v_addc_co_u32_e32 v55, vcc, 0, v43, vcc
	global_store_short v[54:55], v0, off offset:2560
	s_waitcnt lgkmcnt(1)
	v_mul_f32_e32 v0, v38, v46
	s_waitcnt lgkmcnt(0)
	v_fmac_f32_e32 v0, v30, v50
	v_cvt_pk_bf16_f32 v0, v0, s0
	s_mov_b32 s0, 0xfa0000
	v_add_co_u32_e32 v54, vcc, s0, v42
	s_nop 1
	v_addc_co_u32_e32 v55, vcc, 0, v43, vcc
	global_store_short v[54:55], v0, off offset:2560
	v_mul_f32_e32 v0, v39, v47
	v_fmac_f32_e32 v0, v31, v51
	v_cvt_pk_bf16_f32 v0, v0, s0
	s_mov_b32 s0, 0xfa2000
	v_add_co_u32_e32 v30, vcc, s0, v42
	s_nop 1
	v_addc_co_u32_e32 v31, vcc, 0, v43, vcc
	global_store_short v[30:31], v0, off offset:2560
	v_mul_f32_e32 v0, v40, v48
	v_fmac_f32_e32 v0, v32, v52
	v_cvt_pk_bf16_f32 v0, v0, s0
	s_mov_b32 s0, 0xfa4000
	v_add_co_u32_e32 v30, vcc, s0, v42
	s_nop 1
	v_addc_co_u32_e32 v31, vcc, 0, v43, vcc
	global_store_short v[30:31], v0, off offset:2560
	v_mul_f32_e32 v0, v41, v49
	v_fmac_f32_e32 v0, v33, v53
	ds_read_b128 v[30:33], v103 offset:37504
	ds_read_b128 v[38:41], v103 offset:37248
	v_cvt_pk_bf16_f32 v0, v0, s0
	s_mov_b32 s0, 0xfa6000
	v_add_co_u32_e32 v46, vcc, s0, v42
	s_nop 1
	v_addc_co_u32_e32 v47, vcc, 0, v43, vcc
	global_store_short v[46:47], v0, off offset:2560
	s_waitcnt lgkmcnt(1)
	v_mul_f32_e32 v0, v34, v30
	s_waitcnt lgkmcnt(0)
	v_fmac_f32_e32 v0, v26, v38
	v_cvt_pk_bf16_f32 v0, v0, s0
	s_mov_b32 s0, 0xfc0000
	v_add_co_u32_e32 v46, vcc, s0, v42
	s_nop 1
	v_addc_co_u32_e32 v47, vcc, 0, v43, vcc
	global_store_short v[46:47], v0, off offset:2560
	v_mul_f32_e32 v0, v35, v31
	v_fmac_f32_e32 v0, v27, v39
	v_cvt_pk_bf16_f32 v0, v0, s0
	s_mov_b32 s0, 0xfc2000
	v_add_co_u32_e32 v26, vcc, s0, v42
	s_nop 1
	v_addc_co_u32_e32 v27, vcc, 0, v43, vcc
	global_store_short v[26:27], v0, off offset:2560
	v_mul_f32_e32 v0, v36, v32
	v_fmac_f32_e32 v0, v28, v40
	v_cvt_pk_bf16_f32 v0, v0, s0
	s_mov_b32 s0, 0xfc4000
	v_add_co_u32_e32 v26, vcc, s0, v42
	s_nop 1
	v_addc_co_u32_e32 v27, vcc, 0, v43, vcc
	global_store_short v[26:27], v0, off offset:2560
	v_mul_f32_e32 v0, v37, v33
	v_fmac_f32_e32 v0, v29, v41
	ds_read_b128 v[26:29], v103 offset:37568
	ds_read_b128 v[30:33], v103 offset:37312
	v_cvt_pk_bf16_f32 v0, v0, s0
	s_mov_b32 s0, 0xfc6000
	v_add_co_u32_e32 v34, vcc, s0, v42
	s_nop 1
	v_addc_co_u32_e32 v35, vcc, 0, v43, vcc
	global_store_short v[34:35], v0, off offset:2560
	s_waitcnt lgkmcnt(1)
	v_mul_f32_e32 v0, v6, v26
	s_waitcnt lgkmcnt(0)
	v_fmac_f32_e32 v0, v2, v30
	v_cvt_pk_bf16_f32 v0, v0, s0
	s_mov_b32 s0, 0xfe0000
	v_add_co_u32_e32 v34, vcc, s0, v42
	s_nop 1
	v_addc_co_u32_e32 v35, vcc, 0, v43, vcc
	global_store_short v[34:35], v0, off offset:2560
	v_mul_f32_e32 v0, v7, v27
	v_fmac_f32_e32 v0, v3, v31
	v_cvt_pk_bf16_f32 v0, v0, s0
	s_mov_b32 s0, 0xfe2000
	v_add_co_u32_e32 v2, vcc, s0, v42
	s_nop 1
	v_addc_co_u32_e32 v3, vcc, 0, v43, vcc
	global_store_short v[2:3], v0, off offset:2560
	v_mul_f32_e32 v0, v8, v28
	v_fmac_f32_e32 v0, v4, v32
	v_cvt_pk_bf16_f32 v0, v0, s0
	s_mov_b32 s0, 0xfe4000
	v_add_co_u32_e32 v2, vcc, s0, v42
	s_nop 1
	v_addc_co_u32_e32 v3, vcc, 0, v43, vcc
	global_store_short v[2:3], v0, off offset:2560
	v_mul_f32_e32 v0, v9, v29
	v_fmac_f32_e32 v0, v5, v33
	v_cvt_pk_bf16_f32 v0, v0, s0
	s_mov_b32 s0, 0xfe6000
	v_add_co_u32_e32 v6, vcc, s0, v42
	v_readlane_b32 s0, v239, 53
	v_max_f32_e32 v2, v125, v125
	s_lshl_b32 s0, s0, 3
	v_max_f32_e32 v3, v44, v2
	s_add_i32 s0, s38, s0
	v_sub_f32_e32 v2, v125, v3
	s_ashr_i32 s1, s0, 31
	v_sub_f32_e32 v4, v83, v3
	v_mul_f32_e32 v2, 0x3fb8aa3b, v2
	s_lshl_b64 s[38:39], s[0:1], 16
	v_exp_f32_e32 v2, v2
	v_mul_f32_e32 v4, 0x3fb8aa3b, v4
	s_add_u32 s2, s2, s38
	v_exp_f32_e32 v4, v4
	s_addc_u32 s39, s4, s39
	s_lshl_b32 s38, s40, 14
	s_add_u32 s38, s2, s38
	v_addc_co_u32_e32 v7, vcc, 0, v43, vcc
	s_addc_u32 s39, s39, 0
	global_store_short v[6:7], v0, off offset:2560
	v_pk_mul_f32 v[6:7], v[2:3], v[12:13] op_sel_hi:[0,1]
	v_pk_mul_f32 v[8:9], v[2:3], v[10:11] op_sel_hi:[0,1]
	v_pk_mul_f32 v[12:13], v[2:3], v[14:15] op_sel_hi:[0,1]
	v_pk_mul_f32 v[14:15], v[2:3], v[20:21] op_sel_hi:[0,1]
	v_pk_mul_f32 v[20:21], v[2:3], v[22:23] op_sel_hi:[0,1]
	v_lshl_add_u64 v[22:23], v[80:81], 2, s[38:39]
	v_lshlrev_b32_e32 v0, 10, v101
	v_pk_fma_f32 v[6:7], v[4:5], v[98:99], v[6:7] op_sel_hi:[0,1,1]
	v_pk_fma_f32 v[8:9], v[4:5], v[96:97], v[8:9] op_sel_hi:[0,1,1]
	v_lshl_add_u64 v[22:23], v[22:23], 0, v[0:1]
	s_barrier
	global_store_dword v[22:23], v8, off
	global_store_dword v[22:23], v9, off offset:256
	global_store_dword v[22:23], v6, off offset:512
	global_store_dword v[22:23], v7, off offset:768
	v_add_co_u32_e32 v6, vcc, s93, v22
	v_pk_mul_f32 v[10:11], v[2:3], v[16:17] op_sel_hi:[0,1]
	s_nop 0
	v_addc_co_u32_e32 v7, vcc, 0, v23, vcc
	v_add_co_u32_e32 v8, vcc, s94, v22
	v_pk_fma_f32 v[12:13], v[4:5], v[92:93], v[12:13] op_sel_hi:[0,1,1]
	v_pk_mul_f32 v[16:17], v[2:3], v[18:19] op_sel_hi:[0,1]
	v_addc_co_u32_e32 v9, vcc, 0, v23, vcc
	v_pk_fma_f32 v[10:11], v[4:5], v[94:95], v[10:11] op_sel_hi:[0,1,1]
	v_pk_fma_f32 v[14:15], v[4:5], v[90:91], v[14:15] op_sel_hi:[0,1,1]
	v_pk_fma_f32 v[16:17], v[4:5], v[88:89], v[16:17] op_sel_hi:[0,1,1]
	global_store_dword v[8:9], v12, off offset:-4096
	global_store_dword v[6:7], v13, off offset:256
	global_store_dword v[6:7], v10, off offset:512
	global_store_dword v[6:7], v11, off offset:768
	global_store_dword v[8:9], v16, off
	global_store_dword v[8:9], v17, off offset:256
	global_store_dword v[8:9], v14, off offset:512
	global_store_dword v[8:9], v15, off offset:768
	v_add_co_u32_e32 v6, vcc, 0x3000, v22
	v_pk_mul_f32 v[18:19], v[2:3], v[24:25] op_sel_hi:[0,1]
	s_nop 0
	v_addc_co_u32_e32 v7, vcc, 0, v23, vcc
	v_pk_fma_f32 v[20:21], v[4:5], v[84:85], v[20:21] op_sel_hi:[0,1,1]
	v_cmp_gt_u32_e32 vcc, 64, v79
	v_pk_fma_f32 v[18:19], v[4:5], v[86:87], v[18:19] op_sel_hi:[0,1,1]
	global_store_dword v[6:7], v20, off
	global_store_dword v[6:7], v21, off offset:256
	global_store_dword v[6:7], v18, off offset:512
	global_store_dword v[6:7], v19, off offset:768
	s_and_saveexec_b64 s[38:39], vcc
	s_cbranch_execz .LBB0_469
	s_lshl_b64 s[42:43], s[0:1], 10
	s_add_u32 s1, s24, s42
	s_addc_u32 s2, s25, s43
	s_lshl_b32 s41, s40, 8
	v_mov_b32_e32 v83, v119
	v_mov_b32_e32 v5, v2
	s_add_u32 s42, s1, s41
	v_pk_mul_f32 v[4:5], v[82:83], v[4:5]
	s_addc_u32 s43, s2, 0
	v_lshlrev_b32_e32 v0, 2, v78
	v_add_f32_e32 v2, v4, v5
	v_lshl_add_u64 v[4:5], s[42:43], 0, v[0:1]
	v_add_co_u32_e32 v4, vcc, 0x4950000, v4
	s_nop 1
	v_addc_co_u32_e32 v5, vcc, 0, v5, vcc
	v_cmp_eq_u32_e32 vcc, 0, v78
	global_store_dword v[4:5], v2, off
	s_and_b64 exec, exec, vcc
	s_cbranch_execz .LBB0_469
	s_mul_hi_i32 s41, s0, 0xfffffc10
	s_mulk_i32 s0, 0xfc10
	s_add_u32 s0, s1, s0
	s_addc_u32 s1, s2, s41
	s_lshl_b32 s2, s40, 2
	s_add_u32 s0, s0, s2
	s_waitcnt vmcnt(49)
	v_add_f32_e32 v0, v117, v3
	s_addc_u32 s1, s1, 0
	global_store_dword v147, v0, s[0:1]

.Lk2_chunk:
	s_waitcnt vmcnt(16)
	ds_write_b128 v246, v[66:69]
	ds_write_b128 v246, v[82:85] offset:17408
	ds_write_b128 v247, v[106:109] offset:44032
	ds_write_b128 v246, v[70:73] offset:4352
	ds_write_b128 v246, v[86:89] offset:21760
	ds_write_b128 v247, v[110:113] offset:48640
	ds_write_b128 v246, v[74:77] offset:8704
	ds_write_b128 v246, v[90:93] offset:26112
	ds_write_b128 v247, v[114:117] offset:53248
	ds_write_b128 v246, v[78:81] offset:13056
	ds_write_b128 v246, v[94:97] offset:30464
	ds_write_b128 v247, v[118:121] offset:57856
	ds_write_b128 v247, v[98:101] offset:34816
	ds_write_b128 v247, v[102:105] offset:39424
	v_lshlrev_b32_e32 v34, 16, v126
	v_mov_b32_e32 v50, 0
	v_lshlrev_b32_e32 v35, 16, v127
	v_mov_b32_e32 v51, 0
	v_lshlrev_b32_e32 v36, 16, v128
	v_mov_b32_e32 v52, 0
	v_lshlrev_b32_e32 v37, 16, v129
	v_mov_b32_e32 v53, 0
	v_lshlrev_b32_e32 v38, 16, v130
	v_mov_b32_e32 v54, 0
	v_lshlrev_b32_e32 v39, 16, v131
	v_mov_b32_e32 v55, 0
	v_lshlrev_b32_e32 v40, 16, v132
	v_mov_b32_e32 v56, 0
	v_lshlrev_b32_e32 v41, 16, v133
	v_mov_b32_e32 v57, 0
	v_lshlrev_b32_e32 v42, 16, v134
	v_mov_b32_e32 v58, 0
	v_lshlrev_b32_e32 v43, 16, v135
	v_mov_b32_e32 v59, 0
	v_lshlrev_b32_e32 v44, 16, v136
	v_mov_b32_e32 v60, 0
	v_lshlrev_b32_e32 v45, 16, v137
	v_mov_b32_e32 v61, 0
	v_lshlrev_b32_e32 v46, 16, v138
	v_mov_b32_e32 v62, 0
	v_lshlrev_b32_e32 v47, 16, v139
	v_mov_b32_e32 v63, 0
	v_lshlrev_b32_e32 v48, 16, v140
	v_mov_b32_e32 v64, 0
	v_lshlrev_b32_e32 v49, 16, v141
	v_mov_b32_e32 v65, 0
	s_waitcnt lgkmcnt(0)
	s_barrier
	global_load_dword v254, v1, s[42:43]
	s_add_u32 s42, s42, 4
	s_addc_u32 s43, s43, 0
	ds_read_b64 v[164:165], v248 offset:0
	ds_read_b64 v[166:167], v248 offset:32
	ds_read_b64 v[168:169], v248 offset:17408
	ds_read_b64 v[170:171], v248 offset:17440
	ds_read_b64 v[172:173], v248 offset:4352
	ds_read_b64 v[174:175], v248 offset:4384
	ds_read_b64 v[176:177], v248 offset:21760
	ds_read_b64 v[178:179], v248 offset:21792
	ds_read_b64 v[180:181], v248 offset:8704
	ds_read_b64 v[182:183], v248 offset:8736
	ds_read_b64 v[184:185], v248 offset:26112
	ds_read_b64 v[186:187], v248 offset:26144
	ds_read_b64 v[188:189], v248 offset:13056
	ds_read_b64 v[190:191], v248 offset:13088
	v_cvt_pk_bf16_f32 v196, v2, v3
	v_cvt_pk_bf16_f32 v197, v4, v5
	v_cvt_pk_bf16_f32 v198, v6, v7
	v_cvt_pk_bf16_f32 v199, v8, v9
	s_nop 1
	s_waitcnt lgkmcnt(12)
	v_mfma_f32_16x16x32_bf16 v[34:37], v[164:167], v[196:199], v[34:37]
	global_load_dwordx4 v[66:69], v200, s[4:5] offset:1024
	ds_read_b64 v[192:193], v248 offset:30464
	ds_read_b64 v[194:195], v248 offset:30496
	s_waitcnt lgkmcnt(12)
	v_mfma_f32_16x16x32_bf16 v[50:53], v[168:171], v[196:199], v[50:53]
	global_load_dwordx4 v[82:85], v200, s[4:5]
	ds_read_b64 v[164:165], v248 offset:64
	ds_read_b64 v[166:167], v248 offset:96
	s_waitcnt lgkmcnt(12)
	v_mfma_f32_16x16x32_bf16 v[38:41], v[172:175], v[196:199], v[38:41]
	global_load_dwordx4 v[106:109], v204, s[38:39]
	ds_read_b64 v[168:169], v248 offset:17472
	ds_read_b64 v[170:171], v248 offset:17504
	s_waitcnt lgkmcnt(12)
	v_mfma_f32_16x16x32_bf16 v[54:57], v[176:179], v[196:199], v[54:57]
	global_load_dwordx4 v[70:73], v201, s[4:5] offset:1024
	ds_read_b64 v[172:173], v248 offset:4416
	ds_read_b64 v[174:175], v248 offset:4448
	s_waitcnt lgkmcnt(12)
	v_mfma_f32_16x16x32_bf16 v[42:45], v[180:183], v[196:199], v[42:45]
	global_load_dwordx4 v[86:89], v201, s[4:5]
	ds_read_b64 v[176:177], v248 offset:21824
	ds_read_b64 v[178:179], v248 offset:21856
	s_waitcnt lgkmcnt(12)
	v_mfma_f32_16x16x32_bf16 v[58:61], v[184:187], v[196:199], v[58:61]
	global_load_dwordx4 v[110:113], v205, s[38:39]
	ds_read_b64 v[180:181], v248 offset:8768
	ds_read_b64 v[182:183], v248 offset:8800
	s_waitcnt lgkmcnt(12)
	v_mfma_f32_16x16x32_bf16 v[46:49], v[188:191], v[196:199], v[46:49]
	global_load_dwordx4 v[74:77], v202, s[4:5] offset:1024
	ds_read_b64 v[184:185], v248 offset:26176
	ds_read_b64 v[186:187], v248 offset:26208
	s_waitcnt lgkmcnt(12)
	v_mfma_f32_16x16x32_bf16 v[62:65], v[192:195], v[196:199], v[62:65]
	global_load_dwordx4 v[90:93], v202, s[4:5]
	ds_read_b64 v[188:189], v248 offset:13120
	ds_read_b64 v[190:191], v248 offset:13152
	v_cvt_pk_bf16_f32 v196, v10, v11
	v_cvt_pk_bf16_f32 v197, v12, v13
	v_cvt_pk_bf16_f32 v198, v14, v15
	v_cvt_pk_bf16_f32 v199, v16, v17
	s_nop 1
	s_waitcnt lgkmcnt(12)
	v_mfma_f32_16x16x32_bf16 v[34:37], v[164:167], v[196:199], v[34:37]
	global_load_dwordx4 v[114:117], v206, s[38:39]
	ds_read_b64 v[192:193], v248 offset:30528
	ds_read_b64 v[194:195], v248 offset:30560
	s_waitcnt lgkmcnt(12)
	v_mfma_f32_16x16x32_bf16 v[50:53], v[168:171], v[196:199], v[50:53]
	global_load_dwordx4 v[78:81], v203, s[4:5] offset:1024
	ds_read_b64 v[164:165], v248 offset:128
	ds_read_b64 v[166:167], v248 offset:160
	s_waitcnt lgkmcnt(12)
	v_mfma_f32_16x16x32_bf16 v[38:41], v[172:175], v[196:199], v[38:41]
	global_load_dwordx4 v[94:97], v203, s[4:5]
	ds_read_b64 v[168:169], v248 offset:17536
	ds_read_b64 v[170:171], v248 offset:17568
	s_waitcnt lgkmcnt(12)
	v_mfma_f32_16x16x32_bf16 v[54:57], v[176:179], v[196:199], v[54:57]
	global_load_dwordx4 v[118:121], v207, s[38:39]
	ds_read_b64 v[172:173], v248 offset:4480
	ds_read_b64 v[174:175], v248 offset:4512
	s_waitcnt lgkmcnt(12)
	v_mfma_f32_16x16x32_bf16 v[42:45], v[180:183], v[196:199], v[42:45]
	global_load_dwordx4 v[98:101], v208, s[38:39]
	ds_read_b64 v[176:177], v248 offset:21888
	ds_read_b64 v[178:179], v248 offset:21920
	s_waitcnt lgkmcnt(12)
	v_mfma_f32_16x16x32_bf16 v[58:61], v[184:187], v[196:199], v[58:61]
	global_load_dwordx4 v[102:105], v209, s[38:39]
	ds_read_b64 v[180:181], v248 offset:8832
	ds_read_b64 v[182:183], v248 offset:8864
	s_waitcnt lgkmcnt(12)
	v_mfma_f32_16x16x32_bf16 v[46:49], v[188:191], v[196:199], v[46:49]
	global_load_ushort v126, v210, s[4:5]
	ds_read_b64 v[184:185], v248 offset:26240
	ds_read_b64 v[186:187], v248 offset:26272
	s_waitcnt lgkmcnt(12)
	v_mfma_f32_16x16x32_bf16 v[62:65], v[192:195], v[196:199], v[62:65]
	global_load_ushort v127, v211, s[4:5]
	ds_read_b64 v[188:189], v248 offset:13184
	ds_read_b64 v[190:191], v248 offset:13216
	v_cvt_pk_bf16_f32 v196, v18, v19
	v_cvt_pk_bf16_f32 v197, v20, v21
	v_cvt_pk_bf16_f32 v198, v22, v23
	v_cvt_pk_bf16_f32 v199, v24, v25
	s_nop 1
	s_waitcnt lgkmcnt(12)
	v_mfma_f32_16x16x32_bf16 v[34:37], v[164:167], v[196:199], v[34:37]
	global_load_ushort v128, v212, s[4:5]
	ds_read_b64 v[192:193], v248 offset:30592
	ds_read_b64 v[194:195], v248 offset:30624
	s_waitcnt lgkmcnt(12)
	v_mfma_f32_16x16x32_bf16 v[50:53], v[168:171], v[196:199], v[50:53]
	global_load_ushort v129, v213, s[4:5]
	ds_read_b64 v[164:165], v248 offset:192
	ds_read_b64 v[166:167], v248 offset:224
	s_waitcnt lgkmcnt(12)
	v_mfma_f32_16x16x32_bf16 v[38:41], v[172:175], v[196:199], v[38:41]
	global_load_ushort v130, v214, s[4:5]
	ds_read_b64 v[168:169], v248 offset:17600
	ds_read_b64 v[170:171], v248 offset:17632
	s_waitcnt lgkmcnt(12)
	v_mfma_f32_16x16x32_bf16 v[54:57], v[176:179], v[196:199], v[54:57]
	global_load_ushort v131, v215, s[4:5]
	ds_read_b64 v[172:173], v248 offset:4544
	ds_read_b64 v[174:175], v248 offset:4576
	s_waitcnt lgkmcnt(12)
	v_mfma_f32_16x16x32_bf16 v[42:45], v[180:183], v[196:199], v[42:45]
	global_load_ushort v132, v216, s[4:5]
	ds_read_b64 v[176:177], v248 offset:21952
	ds_read_b64 v[178:179], v248 offset:21984
	s_waitcnt lgkmcnt(12)
	v_mfma_f32_16x16x32_bf16 v[58:61], v[184:187], v[196:199], v[58:61]
	global_load_ushort v133, v217, s[4:5]
	ds_read_b64 v[180:181], v248 offset:8896
	ds_read_b64 v[182:183], v248 offset:8928
	s_waitcnt lgkmcnt(12)
	v_mfma_f32_16x16x32_bf16 v[46:49], v[188:191], v[196:199], v[46:49]
	global_load_ushort v134, v218, s[4:5]
	ds_read_b64 v[184:185], v248 offset:26304
	ds_read_b64 v[186:187], v248 offset:26336
	s_waitcnt lgkmcnt(12)
	v_mfma_f32_16x16x32_bf16 v[62:65], v[192:195], v[196:199], v[62:65]
	global_load_ushort v135, v219, s[4:5]
	ds_read_b64 v[188:189], v248 offset:13248
	ds_read_b64 v[190:191], v248 offset:13280
	v_cvt_pk_bf16_f32 v196, v26, v27
	v_cvt_pk_bf16_f32 v197, v28, v29
	v_cvt_pk_bf16_f32 v198, v30, v31
	v_cvt_pk_bf16_f32 v199, v32, v33
	s_nop 1
	s_waitcnt lgkmcnt(12)
	v_mfma_f32_16x16x32_bf16 v[34:37], v[164:167], v[196:199], v[34:37]
	global_load_ushort v136, v220, s[4:5]
	ds_read_b64 v[192:193], v248 offset:30656
	ds_read_b64 v[194:195], v248 offset:30688
	s_waitcnt lgkmcnt(12)
	v_mfma_f32_16x16x32_bf16 v[50:53], v[168:171], v[196:199], v[50:53]
	global_load_ushort v137, v221, s[4:5]
	ds_read_b64 v[164:165], v249 offset:34816
	ds_read_b64 v[166:167], v249 offset:34848
	s_waitcnt lgkmcnt(12)
	v_mfma_f32_16x16x32_bf16 v[38:41], v[172:175], v[196:199], v[38:41]
	global_load_ushort v138, v222, s[4:5]
	ds_read_b64 v[168:169], v249 offset:37120
	ds_read_b64 v[170:171], v249 offset:37152
	s_waitcnt lgkmcnt(12)
	v_mfma_f32_16x16x32_bf16 v[54:57], v[176:179], v[196:199], v[54:57]
	global_load_ushort v139, v223, s[4:5]
	ds_read_b64 v[172:173], v249 offset:39424
	ds_read_b64 v[174:175], v249 offset:39456
	s_waitcnt lgkmcnt(12)
	v_mfma_f32_16x16x32_bf16 v[42:45], v[180:183], v[196:199], v[42:45]
	global_load_ushort v140, v224, s[4:5]
	ds_read_b64 v[176:177], v249 offset:41728
	ds_read_b64 v[178:179], v249 offset:41760
	s_waitcnt lgkmcnt(12)
	v_mfma_f32_16x16x32_bf16 v[58:61], v[184:187], v[196:199], v[58:61]
	global_load_ushort v141, v225, s[4:5]
	s_cmpk_lt_u32 s2, 30
	s_cselect_b32 s47, 0x30000, 0
	s_cselect_b32 s48, 0x6000, 0
	s_add_u32 s4, s4, s47
	s_addc_u32 s5, s5, 0
	s_add_u32 s38, s38, s48
	s_addc_u32 s39, s39, 0
	ds_read_b64 v[180:181], v249 offset:44032
	ds_read_b64 v[182:183], v249 offset:44064
	s_waitcnt lgkmcnt(12)
	v_mfma_f32_16x16x32_bf16 v[46:49], v[188:191], v[196:199], v[46:49]
	ds_read_b64 v[184:185], v249 offset:46336
	ds_read_b64 v[186:187], v249 offset:46368
	s_waitcnt lgkmcnt(12)
	v_mfma_f32_16x16x32_bf16 v[62:65], v[192:195], v[196:199], v[62:65]
	ds_read_b64 v[188:189], v249 offset:48640
	ds_read_b64 v[190:191], v249 offset:48672
	s_waitcnt vmcnt(30)
	v_mul_f32_e32 v2, v254, v2
	v_mul_f32_e32 v3, v254, v3
	v_mul_f32_e32 v4, v254, v4
	v_mul_f32_e32 v5, v254, v5
	v_mul_f32_e32 v6, v254, v6
	v_mul_f32_e32 v7, v254, v7
	v_mul_f32_e32 v8, v254, v8
	v_mul_f32_e32 v9, v254, v9
	v_mul_f32_e32 v10, v254, v10
	v_mul_f32_e32 v11, v254, v11
	v_mul_f32_e32 v12, v254, v12
	v_mul_f32_e32 v13, v254, v13
	v_mul_f32_e32 v14, v254, v14
	v_mul_f32_e32 v15, v254, v15
	v_mul_f32_e32 v16, v254, v16
	v_mul_f32_e32 v17, v254, v17
	v_mul_f32_e32 v18, v254, v18
	v_mul_f32_e32 v19, v254, v19
	v_mul_f32_e32 v20, v254, v20
	v_mul_f32_e32 v21, v254, v21
	v_mul_f32_e32 v22, v254, v22
	v_mul_f32_e32 v23, v254, v23
	v_mul_f32_e32 v24, v254, v24
	v_mul_f32_e32 v25, v254, v25
	v_mul_f32_e32 v26, v254, v26
	v_mul_f32_e32 v27, v254, v27
	v_mul_f32_e32 v28, v254, v28
	v_mul_f32_e32 v29, v254, v29
	v_mul_f32_e32 v30, v254, v30
	v_mul_f32_e32 v31, v254, v31
	v_mul_f32_e32 v32, v254, v32
	v_mul_f32_e32 v33, v254, v33
	v_cvt_pk_bf16_f32 v196, v34, v35
	v_cvt_pk_bf16_f32 v197, v36, v37
	v_cvt_pk_bf16_f32 v198, v38, v39
	v_cvt_pk_bf16_f32 v199, v40, v41
	s_nop 1
	s_waitcnt lgkmcnt(12)
	v_mfma_f32_16x16x32_bf16 v[50:53], v[164:167], v[196:199], v[50:53]
	ds_read_b64 v[192:193], v249 offset:50944
	ds_read_b64 v[194:195], v249 offset:50976
	s_waitcnt lgkmcnt(12)
	v_mfma_f32_16x16x32_bf16 v[54:57], v[168:171], v[196:199], v[54:57]
	ds_read_b64 v[164:165], v249 offset:53248
	ds_read_b64 v[166:167], v249 offset:53280
	s_waitcnt lgkmcnt(12)
	v_mfma_f32_16x16x32_bf16 v[58:61], v[172:175], v[196:199], v[58:61]
	ds_read_b64 v[168:169], v249 offset:55552
	ds_read_b64 v[170:171], v249 offset:55584
	s_waitcnt lgkmcnt(12)
	v_mfma_f32_16x16x32_bf16 v[62:65], v[176:179], v[196:199], v[62:65]
	ds_read_b64 v[172:173], v249 offset:57856
	ds_read_b64 v[174:175], v249 offset:57888
	s_waitcnt lgkmcnt(12)
	v_mfma_f32_16x16x32_bf16 v[2:5], v[180:183], v[196:199], v[2:5]
	ds_read_b64 v[176:177], v249 offset:60160
	ds_read_b64 v[178:179], v249 offset:60192
	s_waitcnt lgkmcnt(12)
	v_mfma_f32_16x16x32_bf16 v[6:9], v[184:187], v[196:199], v[6:9]
	ds_read_b64 v[180:181], v249 offset:34880
	ds_read_b64 v[182:183], v249 offset:34912
	s_waitcnt lgkmcnt(12)
	v_mfma_f32_16x16x32_bf16 v[10:13], v[188:191], v[196:199], v[10:13]
	ds_read_b64 v[184:185], v249 offset:37184
	ds_read_b64 v[186:187], v249 offset:37216
	s_waitcnt lgkmcnt(12)
	v_mfma_f32_16x16x32_bf16 v[14:17], v[192:195], v[196:199], v[14:17]
	ds_read_b64 v[188:189], v249 offset:39488
	ds_read_b64 v[190:191], v249 offset:39520
	s_waitcnt lgkmcnt(12)
	v_mfma_f32_16x16x32_bf16 v[18:21], v[164:167], v[196:199], v[18:21]
	ds_read_b64 v[192:193], v249 offset:41792
	ds_read_b64 v[194:195], v249 offset:41824
	s_waitcnt lgkmcnt(12)
	v_mfma_f32_16x16x32_bf16 v[22:25], v[168:171], v[196:199], v[22:25]
	ds_read_b64 v[164:165], v249 offset:44096
	ds_read_b64 v[166:167], v249 offset:44128
	s_waitcnt lgkmcnt(12)
	v_mfma_f32_16x16x32_bf16 v[26:29], v[172:175], v[196:199], v[26:29]
	ds_read_b64 v[168:169], v249 offset:46400
	ds_read_b64 v[170:171], v249 offset:46432
	s_waitcnt lgkmcnt(12)
	v_mfma_f32_16x16x32_bf16 v[30:33], v[176:179], v[196:199], v[30:33]
	ds_read_b64 v[172:173], v249 offset:48704
	ds_read_b64 v[174:175], v249 offset:48736
	v_cvt_pk_bf16_f32 v196, v42, v43
	v_cvt_pk_bf16_f32 v197, v44, v45
	v_cvt_pk_bf16_f32 v198, v46, v47
	v_cvt_pk_bf16_f32 v199, v48, v49
	s_nop 1
	s_waitcnt lgkmcnt(12)
	v_mfma_f32_16x16x32_bf16 v[50:53], v[180:183], v[196:199], v[50:53]
	ds_read_b64 v[176:177], v249 offset:51008
	ds_read_b64 v[178:179], v249 offset:51040
	s_waitcnt lgkmcnt(12)
	v_mfma_f32_16x16x32_bf16 v[54:57], v[184:187], v[196:199], v[54:57]
	ds_read_b64 v[180:181], v249 offset:53312
	ds_read_b64 v[182:183], v249 offset:53344
	s_waitcnt lgkmcnt(12)
	v_mfma_f32_16x16x32_bf16 v[58:61], v[188:191], v[196:199], v[58:61]
	ds_read_b64 v[184:185], v249 offset:55616
	ds_read_b64 v[186:187], v249 offset:55648
	s_waitcnt lgkmcnt(12)
	v_mfma_f32_16x16x32_bf16 v[62:65], v[192:195], v[196:199], v[62:65]
	ds_read_b64 v[188:189], v249 offset:57920
	ds_read_b64 v[190:191], v249 offset:57952
	s_waitcnt lgkmcnt(12)
	v_mfma_f32_16x16x32_bf16 v[2:5], v[164:167], v[196:199], v[2:5]
	ds_read_b64 v[192:193], v249 offset:60224
	ds_read_b64 v[194:195], v249 offset:60256
	s_waitcnt lgkmcnt(12)
	v_mfma_f32_16x16x32_bf16 v[6:9], v[168:171], v[196:199], v[6:9]
	s_waitcnt lgkmcnt(10)
	v_mfma_f32_16x16x32_bf16 v[10:13], v[172:175], v[196:199], v[10:13]
	s_waitcnt lgkmcnt(8)
	v_mfma_f32_16x16x32_bf16 v[14:17], v[176:179], v[196:199], v[14:17]
	s_waitcnt lgkmcnt(6)
	v_mfma_f32_16x16x32_bf16 v[18:21], v[180:183], v[196:199], v[18:21]
	s_waitcnt lgkmcnt(4)
	v_mfma_f32_16x16x32_bf16 v[22:25], v[184:187], v[196:199], v[22:25]
	s_waitcnt lgkmcnt(2)
	v_mfma_f32_16x16x32_bf16 v[26:29], v[188:191], v[196:199], v[26:29]
	s_waitcnt lgkmcnt(0)
	v_mfma_f32_16x16x32_bf16 v[30:33], v[192:195], v[196:199], v[30:33]
	s_nop 3
	v_cvt_pk_bf16_f32 v250, v50, v50
	global_store_short v226, v250, s[40:41]
	s_nop 0
	v_cvt_pk_bf16_f32 v250, v51, v51
	global_store_short v227, v250, s[40:41]
	s_nop 0
	v_cvt_pk_bf16_f32 v250, v52, v52
	global_store_short v228, v250, s[40:41]
	s_nop 0
	v_cvt_pk_bf16_f32 v250, v53, v53
	global_store_short v229, v250, s[40:41]
	s_nop 0
	v_cvt_pk_bf16_f32 v250, v54, v54
	global_store_short v230, v250, s[40:41]
	s_nop 0
	v_cvt_pk_bf16_f32 v250, v55, v55
	global_store_short v231, v250, s[40:41]
	s_nop 0
	v_cvt_pk_bf16_f32 v250, v56, v56
	global_store_short v232, v250, s[40:41]
	s_nop 0
	v_cvt_pk_bf16_f32 v250, v57, v57
	global_store_short v233, v250, s[40:41]
	s_nop 0
	v_cvt_pk_bf16_f32 v250, v58, v58
	global_store_short v234, v250, s[40:41]
	s_nop 0
	v_cvt_pk_bf16_f32 v250, v59, v59
	global_store_short v235, v250, s[40:41]
	s_nop 0
	v_cvt_pk_bf16_f32 v250, v60, v60
	global_store_short v236, v250, s[40:41]
	s_nop 0
	v_cvt_pk_bf16_f32 v250, v61, v61
	global_store_short v237, v250, s[40:41]
	s_nop 0
	v_cvt_pk_bf16_f32 v250, v62, v62
	global_store_short v242, v250, s[40:41]
	s_nop 0
	v_cvt_pk_bf16_f32 v250, v63, v63
	global_store_short v243, v250, s[40:41]
	s_nop 0
	v_cvt_pk_bf16_f32 v250, v64, v64
	global_store_short v244, v250, s[40:41]
	s_nop 0
	v_cvt_pk_bf16_f32 v250, v65, v65
	global_store_short v245, v250, s[40:41]
	s_nop 0
	s_add_u32 s40, s40, 0x80000
	s_addc_u32 s41, s41, 0
	s_barrier
	s_add_u32 s2, s2, 1
	s_cmpk_lt_u32 s2, 32
	s_cbranch_scc1 .Lk2_chunk
	v_readlane_b32 s47, v239, 53
	s_lshl_b32 s47, s47, 3
	s_add_u32 s47, s47, s45
	s_lshl_b32 s47, s47, 2
	s_add_u32 s47, s47, s44
	s_lshl_b32 s47, s47, 16
	s_add_u32 s47, s47, 0x4450000
	s_add_u32 s40, s24, s47
	s_addc_u32 s41, s25, 0
	v_lshlrev_b32_e32 v250, 9, v143
	v_lshl_add_u32 v250, v142, 2, v250
	s_nop 7
	global_store_dword v250, v2, s[40:41] offset:0 nt
	global_store_dword v250, v3, s[40:41] offset:512 nt
	global_store_dword v250, v4, s[40:41] offset:1024 nt
	global_store_dword v250, v5, s[40:41] offset:1536 nt
	v_add_u32_e32 v250, 0x2000, v250
	global_store_dword v250, v6, s[40:41] offset:0 nt
	global_store_dword v250, v7, s[40:41] offset:512 nt
	global_store_dword v250, v8, s[40:41] offset:1024 nt
	global_store_dword v250, v9, s[40:41] offset:1536 nt
	v_add_u32_e32 v250, 0x2000, v250
	global_store_dword v250, v10, s[40:41] offset:0 nt
	global_store_dword v250, v11, s[40:41] offset:512 nt
	global_store_dword v250, v12, s[40:41] offset:1024 nt
	global_store_dword v250, v13, s[40:41] offset:1536 nt
	v_add_u32_e32 v250, 0x2000, v250
	global_store_dword v250, v14, s[40:41] offset:0 nt
	global_store_dword v250, v15, s[40:41] offset:512 nt
	global_store_dword v250, v16, s[40:41] offset:1024 nt
	global_store_dword v250, v17, s[40:41] offset:1536 nt
	v_add_u32_e32 v250, 0x2000, v250
	global_store_dword v250, v18, s[40:41] offset:0 nt
	global_store_dword v250, v19, s[40:41] offset:512 nt
	global_store_dword v250, v20, s[40:41] offset:1024 nt
	global_store_dword v250, v21, s[40:41] offset:1536 nt
	v_add_u32_e32 v250, 0x2000, v250
	global_store_dword v250, v22, s[40:41] offset:0 nt
	global_store_dword v250, v23, s[40:41] offset:512 nt
	global_store_dword v250, v24, s[40:41] offset:1024 nt
	global_store_dword v250, v25, s[40:41] offset:1536 nt
	v_add_u32_e32 v250, 0x2000, v250
	global_store_dword v250, v26, s[40:41] offset:0 nt
	global_store_dword v250, v27, s[40:41] offset:512 nt
	global_store_dword v250, v28, s[40:41] offset:1024 nt
	global_store_dword v250, v29, s[40:41] offset:1536 nt
	v_add_u32_e32 v250, 0x2000, v250
	global_store_dword v250, v30, s[40:41] offset:0 nt
	global_store_dword v250, v31, s[40:41] offset:512 nt
	global_store_dword v250, v32, s[40:41] offset:1024 nt
	global_store_dword v250, v33, s[40:41] offset:1536 nt
	s_waitcnt vmcnt(0)
